# GEMM tile setup: vmcnt drain of the previous tile's epilogue stores kept only for the E_HG epilogue (the one with unconsumed loads)
# speedup vs baseline: 1.0044x; 1.0044x over previous
.LBB0_637:
	s_and_b64 s[2:3], s[8:9], exec
	v_readlane_b32 s2, v255, 26
	v_readlane_b32 s4, v255, 30
	v_readlane_b32 s3, v255, 27
	v_readlane_b32 s5, v255, 31
	s_cselect_b32 s24, s5, s3
	s_cselect_b32 s28, s4, s2
	v_readlane_b32 s2, v255, 24
	v_readlane_b32 s4, v255, 32
	v_readlane_b32 s3, v255, 25
	v_readlane_b32 s5, v255, 33
	s_cselect_b32 s29, s5, s3
	s_cselect_b32 s34, s4, s2
	v_readlane_b32 s2, v255, 23
	v_readlane_b32 s3, v255, 43
	s_cselect_b32 s14, s3, s2
	v_readlane_b32 s2, v255, 39
	s_cselect_b32 s39, s2, 0
	v_readlane_b32 s2, v255, 18
	v_readlane_b32 s3, v255, 40
	s_cselect_b32 s44, s3, s2
	s_lshl_b32 s45, s15, 8
	s_mul_i32 s2, s15, 0xfe
	s_add_i32 s45, s45, s39
	s_lshl_b32 s6, s47, 8
	s_add_i32 s4, s2, -1
	s_cmp_eq_u32 s44, 7
	s_cselect_b64 vcc, -1, 0
	s_and_b64 s[2:3], vcc, exec
	s_cselect_b32 s2, 0, s45
	s_cselect_b32 s40, s4, 0
	s_ashr_i32 s3, s2, 31
	v_mov_b32_e32 v175, v163
	s_mul_i32 s3, s3, s14
	s_mul_hi_u32 s4, s2, s14
	s_ashr_i32 s7, s6, 31
	s_add_i32 s3, s4, s3
	s_cmp_lg_u32 s44, 6
	s_cbranch_scc1 .Lgemm_tile_nodrain
	s_waitcnt vmcnt(0)
.Lgemm_tile_nodrain:
	v_ashrrev_i32_e32 v10, 6, v175
	v_bfe_u32 v14, v175, 3, 3
	s_mul_i32 s2, s2, s14
	s_mul_i32 s4, s7, s14
	s_mul_hi_u32 s5, s6, s14
	v_lshl_or_b32 v6, v10, 5, v14
	s_add_i32 s5, s5, s4
	v_and_b32_e32 v0, 63, v175
	s_lshl_b64 s[2:3], s[2:3], 1
	s_mul_i32 s4, s6, s14
	s_add_u32 s2, s28, s2
	v_lshlrev_b32_e32 v176, 4, v0
	v_add_u32_e32 v0, s40, v6
	s_addc_u32 s3, s24, s3
	s_lshl_b64 s[4:5], s[4:5], 1
	v_med3_i32 v0, v0, 0, v211
	s_add_u32 s4, s34, s4
	v_cndmask_b32_e32 v0, v6, v0, vcc
	s_addc_u32 s5, s29, s5
	v_bfe_u32 v223, v175, 4, 2
	v_mad_u64_u32 v[166:167], s[28:29], v0, s14, 0
	v_xor_b32_e32 v4, v223, v175
	v_ashrrev_i32_e32 v2, 31, v0
	v_mov_b32_e32 v0, v167
	v_mad_u64_u32 v[2:3], s[28:29], v2, s14, v[0:1]
	v_lshlrev_b32_e32 v0, 3, v4
	v_lshlrev_b32_e32 v15, 2, v10
	v_and_b32_e32 v0, 56, v0
	v_lshlrev_b32_e32 v177, 12, v10
	v_lshlrev_b32_e32 v130, 1, v0
	v_ashrrev_i32_e32 v0, 31, v10
	v_or_b32_e32 v17, v176, v177
	v_or_b32_e32 v18, 1, v15
	v_and_b32_e32 v174, 3, v10
	v_mul_lo_u32 v16, v0, s14
	v_readfirstlane_b32 s15, v17
	v_add_u32_e32 v0, 0x8000, v17
	v_lshl_or_b32 v10, v18, 3, v14
	v_mov_b32_e32 v167, v2
	v_mad_u64_u32 v[168:169], s[28:29], v6, s14, 0
	s_mov_b32 m0, s15
	v_readfirstlane_b32 s15, v0
	v_add_u32_e32 v0, s40, v10
	v_lshl_add_u64 v[2:3], v[166:167], 1, s[2:3]
	v_mov_b32_e32 v131, v1
	v_add_u32_e32 v169, v169, v16
	v_med3_i32 v0, v0, 0, v211
	v_lshl_add_u64 v[4:5], v[2:3], 0, v[130:131]
	v_lshl_add_u64 v[6:7], v[168:169], 1, s[4:5]
	v_cndmask_b32_e32 v0, v10, v0, vcc
	v_lshl_add_u64 v[8:9], v[6:7], 0, v[130:131]
	global_load_lds_dwordx4 v[4:5], off
	s_mov_b32 m0, s15
	v_lshrrev_b32_e32 v4, 1, v10
	v_mad_u64_u32 v[170:171], s[28:29], v0, s14, 0
	global_load_lds_dwordx4 v[8:9], off
	v_xor_b32_e32 v8, v4, v175
	v_ashrrev_i32_e32 v4, 31, v0
	v_mov_b32_e32 v0, v171
	v_mad_u64_u32 v[4:5], s[28:29], v4, s14, v[0:1]
	v_lshlrev_b32_e32 v0, 3, v8
	v_lshlrev_b32_e32 v178, 10, v18
	v_mov_b32_e32 v171, v4
	v_and_b32_e32 v0, 56, v0
	v_mad_u64_u32 v[172:173], s[28:29], v10, s14, 0
	v_or_b32_e32 v18, v176, v178
	v_lshl_add_u64 v[4:5], v[170:171], 1, s[2:3]
	v_lshlrev_b32_e32 v132, 1, v0
	v_mov_b32_e32 v133, v1
	v_add_u32_e32 v173, v173, v16
	v_readfirstlane_b32 s15, v18
	v_add_u32_e32 v0, 0x8000, v18
	v_lshl_add_u64 v[8:9], v[4:5], 0, v[132:133]
	v_lshl_add_u64 v[10:11], v[172:173], 1, s[4:5]
	s_mov_b32 m0, s15
	v_readfirstlane_b32 s15, v0
	s_waitcnt lgkmcnt(0)
	v_lshl_add_u64 v[12:13], v[10:11], 0, v[132:133]
	global_load_lds_dwordx4 v[8:9], off
	s_mov_b32 m0, s15
	v_or_b32_e32 v19, 2, v15
	global_load_lds_dwordx4 v[12:13], off
	v_lshl_or_b32 v12, v19, 3, v14
	v_add_u32_e32 v0, s40, v12
	v_med3_i32 v0, v0, 0, v211
	v_cndmask_b32_e32 v0, v12, v0, vcc
	v_lshrrev_b32_e32 v8, 1, v12
	v_mad_u64_u32 v[154:155], s[28:29], v0, s14, 0
	v_xor_b32_e32 v13, v8, v175
	v_ashrrev_i32_e32 v8, 31, v0
	v_mov_b32_e32 v0, v155
	v_mad_u64_u32 v[8:9], s[28:29], v8, s14, v[0:1]
	v_lshlrev_b32_e32 v0, 3, v13
	v_lshlrev_b32_e32 v179, 10, v19
	v_mov_b32_e32 v155, v8
	v_and_b32_e32 v0, 56, v0
	v_or_b32_e32 v19, v176, v179
	v_lshl_add_u64 v[8:9], v[154:155], 1, s[2:3]
	v_lshlrev_b32_e32 v0, 1, v0
	v_readfirstlane_b32 s15, v19
	v_lshl_add_u64 v[8:9], v[8:9], 0, v[0:1]
	v_mad_u64_u32 v[156:157], s[28:29], v12, s14, 0
	s_mov_b32 m0, s15
	v_add_u32_e32 v157, v157, v16
	global_load_lds_dwordx4 v[8:9], off
	v_add_u32_e32 v8, 0x8000, v19
	v_lshl_add_u64 v[12:13], v[156:157], 1, s[4:5]
	v_readfirstlane_b32 s15, v8
	v_lshl_add_u64 v[12:13], v[12:13], 0, v[0:1]
	s_mov_b32 m0, s15
	v_or_b32_e32 v15, 3, v15
	global_load_lds_dwordx4 v[12:13], off
	v_lshl_or_b32 v12, v15, 3, v14
	v_add_u32_e32 v8, s40, v12
	v_med3_i32 v8, v8, 0, v211
	v_cndmask_b32_e32 v8, v12, v8, vcc
	v_lshrrev_b32_e32 v9, 1, v12
	v_mad_u64_u32 v[158:159], s[28:29], v8, s14, 0
	v_xor_b32_e32 v13, v9, v175
	v_ashrrev_i32_e32 v9, 31, v8
	v_mov_b32_e32 v8, v159
	v_mad_u64_u32 v[8:9], s[28:29], v9, s14, v[8:9]
	v_lshlrev_b32_e32 v13, 3, v13
	v_lshlrev_b32_e32 v180, 10, v15
	v_mov_b32_e32 v159, v8
	v_and_b32_e32 v13, 56, v13
	v_or_b32_e32 v14, v176, v180
	v_lshl_add_u64 v[8:9], v[158:159], 1, s[2:3]
	v_lshlrev_b32_e32 v160, 1, v13
	v_mov_b32_e32 v161, v1
	v_readfirstlane_b32 s15, v14
	v_lshl_add_u64 v[8:9], v[8:9], 0, v[160:161]
	v_mad_u64_u32 v[164:165], s[28:29], v12, s14, 0
	s_mov_b32 m0, s15
	v_add_u32_e32 v165, v165, v16
	global_load_lds_dwordx4 v[8:9], off
	v_add_u32_e32 v8, 0x8000, v14
	s_cmpk_gt_u32 s14, 0x7f
	v_lshl_add_u64 v[12:13], v[164:165], 1, s[4:5]
	v_readfirstlane_b32 s15, v8
	s_cselect_b32 s34, 0x80, 0
	v_add_u32_e32 v8, 0x10000, v17
	v_lshl_add_u64 v[12:13], v[12:13], 0, v[160:161]
	s_mov_b32 m0, s15
	v_lshl_add_u64 v[2:3], v[2:3], 0, s[34:35]
	v_readfirstlane_b32 s15, v8
	global_load_lds_dwordx4 v[12:13], off
	v_lshl_add_u64 v[2:3], v[2:3], 0, v[130:131]
	s_mov_b32 m0, s15
	v_mov_b32_e32 v127, 0
	v_mov_b32_e32 v128, 0
	v_mov_b32_e32 v129, 0
	v_mov_b32_e32 v122, 0
	v_mov_b32_e32 v123, 0
	v_mov_b32_e32 v124, 0
	v_mov_b32_e32 v125, 0
	v_mov_b32_e32 v118, 0
	v_mov_b32_e32 v119, 0
	v_mov_b32_e32 v120, 0
	v_mov_b32_e32 v121, 0
	v_mov_b32_e32 v114, 0
	v_mov_b32_e32 v115, 0
	v_mov_b32_e32 v116, 0
	v_mov_b32_e32 v117, 0
	v_mov_b32_e32 v110, 0
	v_mov_b32_e32 v111, 0
	v_mov_b32_e32 v112, 0
	v_mov_b32_e32 v113, 0
	v_mov_b32_e32 v106, 0
	v_mov_b32_e32 v107, 0
	v_mov_b32_e32 v108, 0
	v_mov_b32_e32 v109, 0
	v_mov_b32_e32 v102, 0
	v_mov_b32_e32 v103, 0
	v_mov_b32_e32 v104, 0
	v_mov_b32_e32 v105, 0
	v_mov_b32_e32 v98, 0
	v_mov_b32_e32 v99, 0
	v_mov_b32_e32 v100, 0
	v_mov_b32_e32 v101, 0
	v_mov_b32_e32 v94, 0
	v_mov_b32_e32 v95, 0
	v_mov_b32_e32 v96, 0
	v_mov_b32_e32 v97, 0
	v_mov_b32_e32 v90, 0
	v_mov_b32_e32 v91, 0
	v_mov_b32_e32 v92, 0
	v_mov_b32_e32 v93, 0
	v_mov_b32_e32 v86, 0
	v_mov_b32_e32 v87, 0
	v_mov_b32_e32 v88, 0
	v_mov_b32_e32 v89, 0
	v_mov_b32_e32 v82, 0
	v_mov_b32_e32 v83, 0
	v_mov_b32_e32 v84, 0
	v_mov_b32_e32 v85, 0
	v_mov_b32_e32 v78, 0
	v_mov_b32_e32 v79, 0
	v_mov_b32_e32 v80, 0
	v_mov_b32_e32 v81, 0
	v_mov_b32_e32 v74, 0
	v_mov_b32_e32 v75, 0
	v_mov_b32_e32 v76, 0
	v_mov_b32_e32 v77, 0
	v_mov_b32_e32 v70, 0
	v_mov_b32_e32 v71, 0
	v_mov_b32_e32 v72, 0
	v_mov_b32_e32 v73, 0
	v_mov_b32_e32 v66, 0
	v_mov_b32_e32 v67, 0
	v_mov_b32_e32 v68, 0
	v_mov_b32_e32 v69, 0
	v_mov_b32_e32 v62, 0
	v_mov_b32_e32 v63, 0
	v_mov_b32_e32 v64, 0
	v_mov_b32_e32 v65, 0
	v_mov_b32_e32 v58, 0
	v_mov_b32_e32 v59, 0
	v_mov_b32_e32 v60, 0
	v_mov_b32_e32 v61, 0
	v_mov_b32_e32 v54, 0
	v_mov_b32_e32 v55, 0
	v_mov_b32_e32 v56, 0
	v_mov_b32_e32 v57, 0
	v_mov_b32_e32 v50, 0
	v_mov_b32_e32 v51, 0
	v_mov_b32_e32 v52, 0
	v_mov_b32_e32 v53, 0
	v_mov_b32_e32 v46, 0
	v_mov_b32_e32 v47, 0
	v_mov_b32_e32 v48, 0
	v_mov_b32_e32 v49, 0
	v_mov_b32_e32 v42, 0
	v_mov_b32_e32 v43, 0
	v_mov_b32_e32 v44, 0
	v_mov_b32_e32 v45, 0
	v_mov_b32_e32 v34, 0
	v_mov_b32_e32 v35, 0
	v_mov_b32_e32 v36, 0
	v_mov_b32_e32 v37, 0
	v_mov_b32_e32 v30, 0
	v_mov_b32_e32 v31, 0
	v_mov_b32_e32 v32, 0
	v_mov_b32_e32 v33, 0
	v_mov_b32_e32 v38, 0
	v_mov_b32_e32 v39, 0
	v_mov_b32_e32 v40, 0
	v_mov_b32_e32 v41, 0
	v_mov_b32_e32 v26, 0
	v_mov_b32_e32 v27, 0
	v_mov_b32_e32 v28, 0
	v_mov_b32_e32 v29, 0
	v_mov_b32_e32 v22, 0
	v_mov_b32_e32 v23, 0
	v_mov_b32_e32 v24, 0
	v_mov_b32_e32 v25, 0
	v_mov_b32_e32 v19, 0
	v_mov_b32_e32 v20, 0
	v_mov_b32_e32 v21, 0
	v_mov_b32_e32 v14, 0
	v_mov_b32_e32 v15, 0
	v_mov_b32_e32 v16, 0
	v_mov_b32_e32 v12, 0
	v_mov_b32_e32 v13, 0
	s_waitcnt vmcnt(0)
	s_waitcnt vmcnt(0) lgkmcnt(0)
	s_barrier
	global_load_lds_dwordx4 v[2:3], off
	v_add_u32_e32 v2, 0x18000, v17
	v_lshl_add_u64 v[6:7], v[6:7], 0, s[34:35]
	v_readfirstlane_b32 s15, v2
	v_lshl_add_u64 v[6:7], v[6:7], 0, v[130:131]
	s_mov_b32 m0, s15
	v_lshl_add_u64 v[2:3], v[4:5], 0, s[34:35]
	global_load_lds_dwordx4 v[6:7], off
	v_add_u32_e32 v6, 0x10000, v18
	v_lshl_add_u64 v[2:3], v[2:3], 0, v[132:133]
	v_readfirstlane_b32 s15, v6
	s_mov_b32 m0, s15
	v_lshl_add_u64 v[4:5], v[10:11], 0, s[34:35]
	global_load_lds_dwordx4 v[2:3], off
	v_add_u32_e32 v2, 0x18000, v18
	v_lshl_add_u64 v[4:5], v[4:5], 0, v[132:133]
	v_readfirstlane_b32 s15, v2
	s_mov_b32 m0, s15
	v_and_b32_e32 v134, 15, v175
	global_load_lds_dwordx4 v[4:5], off
	v_ashrrev_i32_e32 v2, 1, v175
	s_movk_i32 s15, 0xff80
	v_mov_b32_e32 v5, 0
	v_and_or_b32 v225, v2, s15, v134
	v_lshlrev_b32_e32 v224, 6, v174
	s_cmp_lt_u32 s14, 64
	v_readlane_b32 s51, v255, 37
	v_readlane_b32 s52, v255, 38
	s_cbranch_scc1 .Lgemm_skip_zero_a
	v_lshrrev_b32_e32 v10, 1, v134
	v_or_b32_e32 v2, v224, v134
	v_lshlrev_b32_e32 v182, 7, v2
	v_xor_b32_e32 v2, v223, v10
	v_lshlrev_b32_e32 v181, 7, v225
	v_lshlrev_b32_e32 v183, 4, v2
	v_or_b32_e32 v11, v181, v183
	v_or_b32_e32 v244, v182, v183
	v_lshl_add_u64 v[2:3], s[4:5], 0, v[132:133]
	v_lshl_add_u64 v[4:5], s[2:3], 0, v[132:133]
	v_lshl_add_u64 v[6:7], s[4:5], 0, v[130:131]
	v_lshl_add_u64 v[8:9], s[2:3], 0, v[130:131]
	ds_read_b128 v[150:153], v11
	ds_read_b128 v[146:149], v11 offset:2048
	ds_read_b128 v[142:145], v244 offset:32768
	ds_read_b128 v[138:141], v244 offset:34816
	ds_read_b128 v[134:137], v244 offset:36864
	ds_read_b128 v[200:203], v11 offset:4096
	ds_read_b128 v[130:133], v244 offset:38912
	ds_read_b128 v[236:239], v11 offset:6144
	s_lshr_b32 s14, s14, 6
	v_bitop3_b32 v10, v223, v10, 4 bitop3:0x36
	v_mov_b32_e32 v126, 0
	s_add_i32 s15, s14, -1
	v_lshlrev_b32_e32 v184, 4, v10
	v_lshl_add_u64 v[166:167], v[166:167], 1, v[8:9]
	v_lshl_add_u64 v[168:169], v[168:169], 1, v[6:7]
	v_lshl_add_u64 v[170:171], v[170:171], 1, v[4:5]
	v_lshl_add_u64 v[172:173], v[172:173], 1, v[2:3]
	s_mov_b32 s24, 0
	s_mov_b32 s28, 0
	v_mov_b32_e32 v161, v1
	v_lshl_add_u64 v[154:155], v[154:155], 1, v[0:1]
	v_lshl_add_u64 v[156:157], v[156:157], 1, v[0:1]
	v_lshl_add_u64 v[158:159], v[158:159], 1, v[160:161]
	v_lshl_add_u64 v[164:165], v[164:165], 1, v[160:161]
	v_readfirstlane_b32 s100, v179
	v_readfirstlane_b32 s101, v180
	v_readfirstlane_b32 s32, v178
	v_readfirstlane_b32 s41, v177
	s_lshl_b32 s32, s32, 16
	s_or_b32 s32, s32, s41
	v_mov_b32_e32 v18, v126
	v_mov_b32_e32 v17, v126
	v_mov_b32_e32 v10, v126
	v_mov_b32_e32 v11, v126
	v_mov_b32_e32 v6, v126
	v_mov_b32_e32 v7, v126
	v_mov_b32_e32 v8, v126
	v_mov_b32_e32 v9, v126
	v_mov_b32_e32 v2, v126
	v_mov_b32_e32 v3, v126
	v_mov_b32_e32 v4, v126
	v_mov_b32_e32 v5, v126
